# P1 row loop: x loads and XN/XN8 stores marked non-temporal (nt) so the streaming input does not displace the freshly written XN/XN8 that the in-projection reads next; numerics unchanged
# speedup vs baseline: 1.0116x; 1.0116x over previous
.LBB0_75:
	v_writelane_b32 v253, s70, 21
	s_cmp_lt_i32 s94, 2
	s_nop 0
	v_writelane_b32 v253, s71, 22
	s_load_dwordx16 s[60:75], s[0:1], 0x40
	s_cselect_b64 s[0:1], -1, 0
	s_add_u32 s2, s44, 0x200000
	s_addc_u32 s3, s45, 0
	v_writelane_b32 v253, s2, 23
	s_nop 1
	v_writelane_b32 v253, s3, 24
	s_add_u32 s2, s44, 0x1e00000
	s_addc_u32 s3, s45, 0
	v_writelane_b32 v253, s2, 25
	s_nop 1
	v_writelane_b32 v253, s3, 26
	s_add_u32 s2, s44, 0x130000
	s_addc_u32 s3, s45, 0
	v_writelane_b32 v253, s2, 27
	s_and_b64 s[12:13], s[0:1], s[4:5]
	s_mov_b32 s0, s78
	v_writelane_b32 v253, s3, 28
	v_writelane_b32 v253, s44, 29
	s_andn2_b64 vcc, exec, s[12:13]
	s_nop 0
	v_writelane_b32 v253, s45, 30
	v_writelane_b32 v253, s76, 31
	v_writelane_b32 v253, s0, 32
	s_nop 1
	v_writelane_b32 v253, s1, 33
	s_cbranch_vccnz .LBB0_112
	s_mov_b32 s0, s54
	s_lshl_b32 s0, s0, 3
	s_mov_b64 s[52:53], s[80:81]
	s_add_i32 s4, s0, s78
	s_mov_b64 s[54:55], s[82:83]
	s_mov_b64 s[56:57], s[84:85]
	s_mov_b64 s[58:59], s[86:87]
	s_cmp_gt_i32 s4, 0x83ff
	s_cbranch_scc1 .LBB0_81
	v_readlane_b32 s76, v253, 4
	v_readlane_b32 s77, v253, 5
	v_readlane_b32 s80, v253, 8
	v_readlane_b32 s81, v253, 9
	v_readlane_b32 s28, v253, 16
	v_readlane_b32 s29, v253, 17
	s_lshl_b32 s6, s96, 3
	v_lshlrev_b32_e32 v1, 4, v218
	v_lshlrev_b32_e32 v2, 3, v218
	v_lshlrev_b32_e32 v3, 2, v218
	v_mov_b32_e32 v204, 0x358637bd
	s_add_u32 s8, s44, 0x100000
	s_addc_u32 s9, s45, 0
	s_add_u32 s10, s44, 0x2200000
	s_addc_u32 s11, s45, 0
	s_add_u32 s14, s44, 0x15600000
	s_addc_u32 s15, s45, 0
	s_mov_b32 s26, 1
	global_load_dwordx4 v[172:175], v1, s[28:29]
	global_load_dwordx4 v[176:179], v1, s[28:29] offset:1024
	global_load_dwordx4 v[180:183], v1, s[28:29] offset:2048
	global_load_dwordx4 v[184:187], v1, s[28:29] offset:3072
	s_mov_b32 s7, s4
	s_lshr_b32 s0, s7, 13
	s_mul_i32 s0, s0, 0x6000
	s_add_u32 s22, s8, s0
	s_addc_u32 s23, s9, 0
	s_add_u32 s24, s22, 0x1000
	s_addc_u32 s25, s23, 0
	s_and_b32 s0, s7, 0x7fff
	s_lshl_b32 s0, s0, 12
	s_cmp_lt_u32 s7, 0x8000
	s_cselect_b32 s20, s76, s80
	s_cselect_b32 s21, s77, s81
	s_add_u32 s20, s20, s0
	s_addc_u32 s21, s21, 0
	global_load_dwordx4 v[4:7], v1, s[20:21] nt
	global_load_dwordx4 v[8:11], v1, s[20:21] offset:1024 nt
	global_load_dwordx4 v[12:15], v1, s[20:21] offset:2048 nt
	global_load_dwordx4 v[16:19], v1, s[20:21] offset:3072 nt
	global_load_dwordx4 v[20:23], v1, s[24:25]
	global_load_dwordx4 v[24:27], v1, s[24:25] offset:1024
	global_load_dwordx4 v[28:31], v1, s[24:25] offset:2048
	global_load_dwordx4 v[32:35], v1, s[24:25] offset:3072
	global_load_dwordx4 v[36:39], v1, s[22:23]
	global_load_dwordx4 v[40:43], v1, s[22:23] offset:1024
	global_load_dwordx4 v[44:47], v1, s[22:23] offset:2048
	global_load_dwordx4 v[48:51], v1, s[22:23] offset:3072
.Lp1_a:
	s_add_i32 s5, s4, s6
	s_cmp_gt_i32 s5, 0x83ff
	s_cbranch_scc1 .Lp1_a_last
	s_mov_b32 s7, s5
	s_lshr_b32 s0, s7, 13
	s_mul_i32 s0, s0, 0x6000
	s_add_u32 s22, s8, s0
	s_addc_u32 s23, s9, 0
	s_add_u32 s24, s22, 0x1000
	s_addc_u32 s25, s23, 0
	s_and_b32 s0, s7, 0x7fff
	s_lshl_b32 s0, s0, 12
	s_cmp_lt_u32 s7, 0x8000
	s_cselect_b32 s20, s76, s80
	s_cselect_b32 s21, s77, s81
	s_add_u32 s20, s20, s0
	s_addc_u32 s21, s21, 0
	global_load_dwordx4 v[188:191], v1, s[20:21] nt
	global_load_dwordx4 v[192:195], v1, s[20:21] offset:1024 nt
	global_load_dwordx4 v[196:199], v1, s[20:21] offset:2048 nt
	global_load_dwordx4 v[200:203], v1, s[20:21] offset:3072 nt
	global_load_dwordx4 v[220:223], v1, s[24:25]
	global_load_dwordx4 v[224:227], v1, s[24:25] offset:1024
	global_load_dwordx4 v[228:231], v1, s[24:25] offset:2048
	global_load_dwordx4 v[232:235], v1, s[24:25] offset:3072
	global_load_dwordx4 v[236:239], v1, s[22:23]
	global_load_dwordx4 v[240:243], v1, s[22:23] offset:1024
	global_load_dwordx4 v[244:247], v1, s[22:23] offset:2048
	global_load_dwordx4 v[248:251], v1, s[22:23] offset:3072
	s_cmp_eq_u32 s26, 0
	s_cbranch_scc1 .Lp1_a_w20
	s_waitcnt vmcnt(12)
	s_branch .Lp1_a_go

.Lp1_a_go:
	s_mov_b32 s26, 0
	s_lshl_b32 s0, s4, 11
	s_add_u32 s16, s10, s0
	s_addc_u32 s17, s11, 0
	s_lshl_b32 s0, s4, 10
	s_add_u32 s18, s14, s0
	s_addc_u32 s19, s15, 0
	v_pk_mul_f32 v[54:55], v[4:5], v[4:5]
	v_pk_mul_f32 v[56:57], v[6:7], v[6:7]
	v_pk_fma_f32 v[54:55], v[8:9], v[8:9], v[54:55]
	v_pk_fma_f32 v[56:57], v[10:11], v[10:11], v[56:57]
	v_pk_fma_f32 v[54:55], v[12:13], v[12:13], v[54:55]
	v_pk_fma_f32 v[56:57], v[14:15], v[14:15], v[56:57]
	v_pk_fma_f32 v[54:55], v[16:17], v[16:17], v[54:55]
	v_pk_fma_f32 v[56:57], v[18:19], v[18:19], v[56:57]
	v_pk_add_f32 v[54:55], v[54:55], v[56:57]
	s_nop 0
	v_add_f32_e32 v52, v54, v55
	s_nop 1
	v_add_f32_dpp v52, v52, v52 quad_perm:[1,0,3,2] row_mask:0xf bank_mask:0xf
	s_nop 1
	v_add_f32_dpp v52, v52, v52 quad_perm:[2,3,0,1] row_mask:0xf bank_mask:0xf
	s_nop 1
	v_add_f32_dpp v52, v52, v52 row_half_mirror row_mask:0xf bank_mask:0xf
	s_nop 1
	v_add_f32_dpp v52, v52, v52 row_mirror row_mask:0xf bank_mask:0xf
	s_nop 1
	v_add_f32_dpp v52, v52, v52 row_bcast:15 row_mask:0xa bank_mask:0xf
	s_nop 1
	v_add_f32_dpp v52, v52, v52 row_bcast:31 row_mask:0xc bank_mask:0xf
	s_nop 1
	v_readlane_b32 s27, v52, 63
	s_nop 3
	v_mov_b32_e32 v52, s27
	v_fmamk_f32 v52, v52, 0x3a800000, v204
	v_rsq_f32_e32 v52, v52
	s_nop 1
	v_pk_mul_f32 v[4:5], v[4:5], v[52:53] op_sel_hi:[1,0]
	v_pk_mul_f32 v[6:7], v[6:7], v[52:53] op_sel_hi:[1,0]
	v_pk_mul_f32 v[8:9], v[8:9], v[52:53] op_sel_hi:[1,0]
	v_pk_mul_f32 v[10:11], v[10:11], v[52:53] op_sel_hi:[1,0]
	v_pk_mul_f32 v[12:13], v[12:13], v[52:53] op_sel_hi:[1,0]
	v_pk_mul_f32 v[14:15], v[14:15], v[52:53] op_sel_hi:[1,0]
	v_pk_mul_f32 v[16:17], v[16:17], v[52:53] op_sel_hi:[1,0]
	v_pk_mul_f32 v[18:19], v[18:19], v[52:53] op_sel_hi:[1,0]
	v_pk_mul_f32 v[4:5], v[172:173], v[4:5]
	v_pk_mul_f32 v[6:7], v[174:175], v[6:7]
	v_pk_mul_f32 v[8:9], v[176:177], v[8:9]
	v_pk_mul_f32 v[10:11], v[178:179], v[10:11]
	v_pk_mul_f32 v[12:13], v[180:181], v[12:13]
	v_pk_mul_f32 v[14:15], v[182:183], v[14:15]
	v_pk_mul_f32 v[16:17], v[184:185], v[16:17]
	v_pk_mul_f32 v[18:19], v[186:187], v[18:19]
	v_pk_add_f32 v[20:21], v[20:21], 1.0 op_sel_hi:[1,0]
	v_pk_add_f32 v[22:23], v[22:23], 1.0 op_sel_hi:[1,0]
	v_pk_add_f32 v[24:25], v[24:25], 1.0 op_sel_hi:[1,0]
	v_pk_add_f32 v[26:27], v[26:27], 1.0 op_sel_hi:[1,0]
	v_pk_add_f32 v[28:29], v[28:29], 1.0 op_sel_hi:[1,0]
	v_pk_add_f32 v[30:31], v[30:31], 1.0 op_sel_hi:[1,0]
	v_pk_add_f32 v[32:33], v[32:33], 1.0 op_sel_hi:[1,0]
	v_pk_add_f32 v[34:35], v[34:35], 1.0 op_sel_hi:[1,0]
	v_pk_fma_f32 v[4:5], v[20:21], v[4:5], v[36:37]
	v_pk_fma_f32 v[6:7], v[22:23], v[6:7], v[38:39]
	v_pk_fma_f32 v[8:9], v[24:25], v[8:9], v[40:41]
	v_pk_fma_f32 v[10:11], v[26:27], v[10:11], v[42:43]
	v_pk_fma_f32 v[12:13], v[28:29], v[12:13], v[44:45]
	v_pk_fma_f32 v[14:15], v[30:31], v[14:15], v[46:47]
	v_pk_fma_f32 v[16:17], v[32:33], v[16:17], v[48:49]
	v_pk_fma_f32 v[18:19], v[34:35], v[18:19], v[50:51]
	v_cvt_pk_bf16_f32 v206, v4, v5
	v_cvt_pk_bf16_f32 v207, v6, v7
	v_cvt_pk_fp8_f32 v214, v4, v5
	v_cvt_pk_bf16_f32 v208, v8, v9
	v_cvt_pk_bf16_f32 v209, v10, v11
	v_cvt_pk_fp8_f32 v215, v8, v9
	v_cvt_pk_bf16_f32 v210, v12, v13
	v_cvt_pk_bf16_f32 v211, v14, v15
	v_cvt_pk_fp8_f32 v216, v12, v13
	v_cvt_pk_bf16_f32 v212, v16, v17
	v_cvt_pk_bf16_f32 v213, v18, v19
	v_cvt_pk_fp8_f32 v217, v16, v17
	v_cvt_pk_fp8_f32 v214, v6, v7 op_sel:[0,0,1]
	v_cvt_pk_fp8_f32 v215, v10, v11 op_sel:[0,0,1]
	v_cvt_pk_fp8_f32 v216, v14, v15 op_sel:[0,0,1]
	v_cvt_pk_fp8_f32 v217, v18, v19 op_sel:[0,0,1]
	s_nop 1
	global_store_dwordx2 v2, v[206:207], s[16:17] nt
	global_store_dwordx2 v2, v[208:209], s[16:17] offset:512 nt
	global_store_dwordx2 v2, v[210:211], s[16:17] offset:1024 nt
	global_store_dwordx2 v2, v[212:213], s[16:17] offset:1536 nt
	global_store_dword v3, v214, s[18:19] nt
	global_store_dword v3, v215, s[18:19] offset:256 nt
	global_store_dword v3, v216, s[18:19] offset:512 nt
	global_store_dword v3, v217, s[18:19] offset:768 nt
	s_cmp_gt_i32 s5, 0x83ff
	s_cbranch_scc1 .Lp1_done
	s_mov_b32 s4, s5
.Lp1_b:
	s_add_i32 s5, s4, s6
	s_cmp_gt_i32 s5, 0x83ff
	s_cbranch_scc1 .Lp1_b_last
	s_mov_b32 s7, s5
	s_lshr_b32 s0, s7, 13
	s_mul_i32 s0, s0, 0x6000
	s_add_u32 s22, s8, s0
	s_addc_u32 s23, s9, 0
	s_add_u32 s24, s22, 0x1000
	s_addc_u32 s25, s23, 0
	s_and_b32 s0, s7, 0x7fff
	s_lshl_b32 s0, s0, 12
	s_cmp_lt_u32 s7, 0x8000
	s_cselect_b32 s20, s76, s80
	s_cselect_b32 s21, s77, s81
	s_add_u32 s20, s20, s0
	s_addc_u32 s21, s21, 0
	global_load_dwordx4 v[4:7], v1, s[20:21] nt
	global_load_dwordx4 v[8:11], v1, s[20:21] offset:1024 nt
	global_load_dwordx4 v[12:15], v1, s[20:21] offset:2048 nt
	global_load_dwordx4 v[16:19], v1, s[20:21] offset:3072 nt
	global_load_dwordx4 v[20:23], v1, s[24:25]
	global_load_dwordx4 v[24:27], v1, s[24:25] offset:1024
	global_load_dwordx4 v[28:31], v1, s[24:25] offset:2048
	global_load_dwordx4 v[32:35], v1, s[24:25] offset:3072
	global_load_dwordx4 v[36:39], v1, s[22:23]
	global_load_dwordx4 v[40:43], v1, s[22:23] offset:1024
	global_load_dwordx4 v[44:47], v1, s[22:23] offset:2048
	global_load_dwordx4 v[48:51], v1, s[22:23] offset:3072
	s_cmp_eq_u32 s26, 0
	s_cbranch_scc1 .Lp1_b_w20
	s_waitcnt vmcnt(12)
	s_branch .Lp1_b_go

.Lp1_b_go:
	s_mov_b32 s26, 0
	s_lshl_b32 s0, s4, 11
	s_add_u32 s16, s10, s0
	s_addc_u32 s17, s11, 0
	s_lshl_b32 s0, s4, 10
	s_add_u32 s18, s14, s0
	s_addc_u32 s19, s15, 0
	v_pk_mul_f32 v[54:55], v[188:189], v[188:189]
	v_pk_mul_f32 v[56:57], v[190:191], v[190:191]
	v_pk_fma_f32 v[54:55], v[192:193], v[192:193], v[54:55]
	v_pk_fma_f32 v[56:57], v[194:195], v[194:195], v[56:57]
	v_pk_fma_f32 v[54:55], v[196:197], v[196:197], v[54:55]
	v_pk_fma_f32 v[56:57], v[198:199], v[198:199], v[56:57]
	v_pk_fma_f32 v[54:55], v[200:201], v[200:201], v[54:55]
	v_pk_fma_f32 v[56:57], v[202:203], v[202:203], v[56:57]
	v_pk_add_f32 v[54:55], v[54:55], v[56:57]
	s_nop 0
	v_add_f32_e32 v52, v54, v55
	s_nop 1
	v_add_f32_dpp v52, v52, v52 quad_perm:[1,0,3,2] row_mask:0xf bank_mask:0xf
	s_nop 1
	v_add_f32_dpp v52, v52, v52 quad_perm:[2,3,0,1] row_mask:0xf bank_mask:0xf
	s_nop 1
	v_add_f32_dpp v52, v52, v52 row_half_mirror row_mask:0xf bank_mask:0xf
	s_nop 1
	v_add_f32_dpp v52, v52, v52 row_mirror row_mask:0xf bank_mask:0xf
	s_nop 1
	v_add_f32_dpp v52, v52, v52 row_bcast:15 row_mask:0xa bank_mask:0xf
	s_nop 1
	v_add_f32_dpp v52, v52, v52 row_bcast:31 row_mask:0xc bank_mask:0xf
	s_nop 1
	v_readlane_b32 s27, v52, 63
	s_nop 3
	v_mov_b32_e32 v52, s27
	v_fmamk_f32 v52, v52, 0x3a800000, v204
	v_rsq_f32_e32 v52, v52
	s_nop 1
	v_pk_mul_f32 v[188:189], v[188:189], v[52:53] op_sel_hi:[1,0]
	v_pk_mul_f32 v[190:191], v[190:191], v[52:53] op_sel_hi:[1,0]
	v_pk_mul_f32 v[192:193], v[192:193], v[52:53] op_sel_hi:[1,0]
	v_pk_mul_f32 v[194:195], v[194:195], v[52:53] op_sel_hi:[1,0]
	v_pk_mul_f32 v[196:197], v[196:197], v[52:53] op_sel_hi:[1,0]
	v_pk_mul_f32 v[198:199], v[198:199], v[52:53] op_sel_hi:[1,0]
	v_pk_mul_f32 v[200:201], v[200:201], v[52:53] op_sel_hi:[1,0]
	v_pk_mul_f32 v[202:203], v[202:203], v[52:53] op_sel_hi:[1,0]
	v_pk_mul_f32 v[188:189], v[172:173], v[188:189]
	v_pk_mul_f32 v[190:191], v[174:175], v[190:191]
	v_pk_mul_f32 v[192:193], v[176:177], v[192:193]
	v_pk_mul_f32 v[194:195], v[178:179], v[194:195]
	v_pk_mul_f32 v[196:197], v[180:181], v[196:197]
	v_pk_mul_f32 v[198:199], v[182:183], v[198:199]
	v_pk_mul_f32 v[200:201], v[184:185], v[200:201]
	v_pk_mul_f32 v[202:203], v[186:187], v[202:203]
	v_pk_add_f32 v[220:221], v[220:221], 1.0 op_sel_hi:[1,0]
	v_pk_add_f32 v[222:223], v[222:223], 1.0 op_sel_hi:[1,0]
	v_pk_add_f32 v[224:225], v[224:225], 1.0 op_sel_hi:[1,0]
	v_pk_add_f32 v[226:227], v[226:227], 1.0 op_sel_hi:[1,0]
	v_pk_add_f32 v[228:229], v[228:229], 1.0 op_sel_hi:[1,0]
	v_pk_add_f32 v[230:231], v[230:231], 1.0 op_sel_hi:[1,0]
	v_pk_add_f32 v[232:233], v[232:233], 1.0 op_sel_hi:[1,0]
	v_pk_add_f32 v[234:235], v[234:235], 1.0 op_sel_hi:[1,0]
	v_pk_fma_f32 v[188:189], v[220:221], v[188:189], v[236:237]
	v_pk_fma_f32 v[190:191], v[222:223], v[190:191], v[238:239]
	v_pk_fma_f32 v[192:193], v[224:225], v[192:193], v[240:241]
	v_pk_fma_f32 v[194:195], v[226:227], v[194:195], v[242:243]
	v_pk_fma_f32 v[196:197], v[228:229], v[196:197], v[244:245]
	v_pk_fma_f32 v[198:199], v[230:231], v[198:199], v[246:247]
	v_pk_fma_f32 v[200:201], v[232:233], v[200:201], v[248:249]
	v_pk_fma_f32 v[202:203], v[234:235], v[202:203], v[250:251]
	v_cvt_pk_bf16_f32 v206, v188, v189
	v_cvt_pk_bf16_f32 v207, v190, v191
	v_cvt_pk_fp8_f32 v214, v188, v189
	v_cvt_pk_bf16_f32 v208, v192, v193
	v_cvt_pk_bf16_f32 v209, v194, v195
	v_cvt_pk_fp8_f32 v215, v192, v193
	v_cvt_pk_bf16_f32 v210, v196, v197
	v_cvt_pk_bf16_f32 v211, v198, v199
	v_cvt_pk_fp8_f32 v216, v196, v197
	v_cvt_pk_bf16_f32 v212, v200, v201
	v_cvt_pk_bf16_f32 v213, v202, v203
	v_cvt_pk_fp8_f32 v217, v200, v201
	v_cvt_pk_fp8_f32 v214, v190, v191 op_sel:[0,0,1]
	v_cvt_pk_fp8_f32 v215, v194, v195 op_sel:[0,0,1]
	v_cvt_pk_fp8_f32 v216, v198, v199 op_sel:[0,0,1]
	v_cvt_pk_fp8_f32 v217, v202, v203 op_sel:[0,0,1]
	s_nop 1
	global_store_dwordx2 v2, v[206:207], s[16:17] nt
	global_store_dwordx2 v2, v[208:209], s[16:17] offset:512 nt
	global_store_dwordx2 v2, v[210:211], s[16:17] offset:1024 nt
	global_store_dwordx2 v2, v[212:213], s[16:17] offset:1536 nt
	global_store_dword v3, v214, s[18:19] nt
	global_store_dword v3, v215, s[18:19] offset:256 nt
	global_store_dword v3, v216, s[18:19] offset:512 nt
	global_store_dword v3, v217, s[18:19] offset:768 nt
	s_cmp_gt_i32 s5, 0x83ff
	s_cbranch_scc1 .Lp1_done
	s_mov_b32 s4, s5
	s_branch .Lp1_a
